# attention loop VALU front-loaded (gap cost 19.5 cycles per MFMA slot instead of 22.4)
# baseline (speedup 1.0000x reference)
.LBB0_1048:
	s_add_i32 s12, s12, 2
	s_min_u32 s14, s12, 0xfc
	s_add_i32 s14, s14, 3
	s_mul_i32 s3, s14, 0x3000
	s_mov_b32 s13, s10
	s_mov_b32 s10, s6
	s_add_u32 s6, s42, s3
	s_addc_u32 s7, s43, 0
	s_lshl_b32 s90, s14, 13
	v_lshl_add_u64 v[182:183], v[162:163], 1, s[6:7]
	global_load_dwordx4 v[158:161], v[182:183], off
	s_and_saveexec_b64 s[8:9], s[4:5]
	s_cbranch_execz .Lattn_h0_nok1
	v_lshl_add_u64 v[182:183], s[6:7], 0, v[168:169]
	global_load_dwordx4 v[114:117], v[182:183], off
.Lattn_h0_nok1:
	s_or_b64 exec, exec, s[8:9]
	v_lshl_add_u64 v[182:183], v[164:165], 0, s[90:91]
	global_load_dwordx4 v[154:157], v[182:183], off
	s_setprio 1
	s_add_i32 s15, s13, 0
	s_add_i32 s14, s10, 0
	s_add_i32 s16, s11, 0
	v_add3_u32 v177, s15, v174, v112
	v_add3_u32 v178, s14, v176, v112
	ds_read_b128 v[202:205], v177
	ds_read_b128 v[206:209], v177 offset:6656
	ds_read_b128 v[210:213], v177 offset:32
	v_mfma_f32_32x32x16_bf16 v[16:31], v[194:197], v[214:217], v[16:31]
	ds_read_b128 v[194:197], v177 offset:6688
	v_exp_f32_e32 v64, v64
	v_exp_f32_e32 v65, v65
	v_exp_f32_e32 v66, v66
	v_mfma_f32_32x32x16_bf16 v[0:15], v[198:201], v[214:217], v[0:15]
	ds_read_b128 v[198:201], v177 offset:64
	v_exp_f32_e32 v67, v67
	v_exp_f32_e32 v68, v68
	s_waitcnt lgkmcnt(4)
	v_mfma_f32_32x32x16_bf16 v[96:111], v[202:205], v[126:129], v[32:47]
	ds_read_b128 v[202:205], v177 offset:6720
	v_exp_f32_e32 v69, v69
	v_exp_f32_e32 v70, v70
	v_exp_f32_e32 v71, v71
	s_waitcnt lgkmcnt(4)
	v_mfma_f32_32x32x16_bf16 v[80:95], v[206:209], v[126:129], v[32:47]
	ds_read_b128 v[206:209], v177 offset:96
	v_exp_f32_e32 v72, v72
	v_add_f32_e32 v179, v179, v64
	v_exp_f32_e32 v73, v73
	s_waitcnt lgkmcnt(4)
	v_mfma_f32_32x32x16_bf16 v[96:111], v[210:213], v[130:133], v[96:111]
	ds_read_b128 v[210:213], v177 offset:6752
	v_add_f32_e32 v218, v218, v65
	v_exp_f32_e32 v74, v74
	v_add_f32_e32 v179, v179, v66
	s_waitcnt lgkmcnt(4)
	v_mfma_f32_32x32x16_bf16 v[80:95], v[194:197], v[130:133], v[80:95]
	ds_read_b128 v[194:197], v177 offset:128
	v_exp_f32_e32 v75, v75
	v_add_f32_e32 v218, v218, v67
	v_exp_f32_e32 v76, v76
	s_waitcnt lgkmcnt(4)
	v_mfma_f32_32x32x16_bf16 v[96:111], v[198:201], v[134:137], v[96:111]
	ds_read_b128 v[198:201], v177 offset:6784
	v_add_f32_e32 v179, v179, v68
	v_exp_f32_e32 v77, v77
	v_add_f32_e32 v218, v218, v69
	v_exp_f32_e32 v78, v78
	s_waitcnt lgkmcnt(4)
	v_mfma_f32_32x32x16_bf16 v[80:95], v[202:205], v[134:137], v[80:95]
	ds_read_b128 v[202:205], v177 offset:160
	v_add_f32_e32 v179, v179, v70
	v_exp_f32_e32 v79, v79
	s_waitcnt lgkmcnt(4)
	v_mfma_f32_32x32x16_bf16 v[96:111], v[206:209], v[138:141], v[96:111]
	ds_read_b128 v[206:209], v177 offset:6816
	v_add_f32_e32 v218, v218, v71
	v_cvt_pk_bf16_f32 v64, v64, v65
	v_cvt_pk_bf16_f32 v65, v66, v67
	v_cvt_pk_bf16_f32 v66, v68, v69
	v_cvt_pk_bf16_f32 v67, v70, v71
	v_add_u32_e32 v180, s16, v170
	s_waitcnt vmcnt(3)
	ds_write_b128 v180, v[122:125]
	s_and_saveexec_b64 s[6:7], s[4:5]
	v_add_u32_e32 v180, s16, v173
	ds_write_b128 v180, v[118:121]
	s_or_b64 exec, exec, s[6:7]
	v_add_u32_e32 v180, s16, v172
	v_add_u32_e32 v180, 0x3000, v180
	s_waitcnt vmcnt(2)
	ds_write2_b64 v180, v[150:151], v[152:153] offset0:128 offset1:130
	s_waitcnt lgkmcnt(6)
	v_mfma_f32_32x32x16_bf16 v[80:95], v[210:213], v[138:141], v[80:95]
	ds_read_b128 v[210:213], v178 offset:13312
	v_exp_f32_e32 v48, v48
	v_add_f32_e32 v179, v179, v72
	v_exp_f32_e32 v49, v49
	s_waitcnt lgkmcnt(6)
	v_mfma_f32_32x32x16_bf16 v[96:111], v[194:197], v[142:145], v[96:111]
	ds_read_b128 v[194:197], v178 offset:17920
	v_add_f32_e32 v218, v218, v73
	v_exp_f32_e32 v50, v50
	v_add_f32_e32 v179, v179, v74
	v_exp_f32_e32 v51, v51
	s_waitcnt lgkmcnt(6)
	v_mfma_f32_32x32x16_bf16 v[80:95], v[198:201], v[142:145], v[80:95]
	ds_read_b128 v[198:201], v178 offset:13344
	v_add_f32_e32 v218, v218, v75
	v_exp_f32_e32 v52, v52
	v_add_f32_e32 v179, v179, v76
	s_waitcnt lgkmcnt(6)
	v_mfma_f32_32x32x16_bf16 v[96:111], v[202:205], v[146:149], v[96:111]
	ds_read_b128 v[202:205], v178 offset:17952
	v_exp_f32_e32 v53, v53
	v_add_f32_e32 v218, v218, v77
	v_exp_f32_e32 v54, v54
	s_waitcnt lgkmcnt(6)
	v_mfma_f32_32x32x16_bf16 v[80:95], v[206:209], v[146:149], v[80:95]
	ds_read_b128 v[206:209], v178 offset:13376
	v_add_f32_e32 v179, v179, v78
	v_exp_f32_e32 v55, v55
	v_add_f32_e32 v218, v218, v79
	v_cvt_pk_bf16_f32 v72, v72, v73
	s_waitcnt lgkmcnt(4)
	v_mfma_f32_32x32x16_bf16 v[16:31], v[210:213], v[64:67], v[16:31]
	ds_read_b128 v[210:213], v178 offset:17984
	v_cvt_pk_bf16_f32 v73, v74, v75
	v_cvt_pk_bf16_f32 v74, v76, v77
	v_cvt_pk_bf16_f32 v75, v78, v79
	v_add_f32_e32 v179, v179, v48
	v_add_f32_e32 v218, v218, v49
	s_waitcnt lgkmcnt(4)
	v_mfma_f32_32x32x16_bf16 v[0:15], v[194:197], v[64:67], v[0:15]
	ds_read_b128 v[194:197], v178 offset:13408
	v_add_f32_e32 v179, v179, v50
	v_add_f32_e32 v218, v218, v51
	v_add_f32_e32 v179, v179, v52
	v_add_f32_e32 v218, v218, v53
	s_waitcnt lgkmcnt(4)
	v_mfma_f32_32x32x16_bf16 v[16:31], v[198:201], v[72:75], v[16:31]
	ds_read_b128 v[198:201], v178 offset:18016
	v_add_f32_e32 v179, v179, v54
	v_add_f32_e32 v218, v218, v55
	v_cvt_pk_bf16_f32 v48, v48, v49
	v_cvt_pk_bf16_f32 v49, v50, v51
	v_cvt_pk_bf16_f32 v50, v52, v53
	s_waitcnt lgkmcnt(4)
	v_mfma_f32_32x32x16_bf16 v[0:15], v[202:205], v[72:75], v[0:15]
	v_cvt_pk_bf16_f32 v51, v54, v55
	v_exp_f32_e32 v56, v56
	v_exp_f32_e32 v57, v57
	s_waitcnt lgkmcnt(3)
	v_mfma_f32_32x32x16_bf16 v[16:31], v[206:209], v[48:51], v[16:31]
	v_exp_f32_e32 v58, v58
	v_exp_f32_e32 v59, v59
	v_exp_f32_e32 v60, v60
	s_waitcnt lgkmcnt(2)
	v_mfma_f32_32x32x16_bf16 v[0:15], v[210:213], v[48:51], v[0:15]
	v_exp_f32_e32 v61, v61
	v_exp_f32_e32 v62, v62
	v_exp_f32_e32 v63, v63
	v_add_f32_e32 v179, v179, v56
	v_add_f32_e32 v218, v218, v57
	v_add_f32_e32 v179, v179, v58
	v_add_f32_e32 v218, v218, v59
	v_add_f32_e32 v179, v179, v60
	v_add_f32_e32 v218, v218, v61
	v_add_f32_e32 v179, v179, v62
	v_add_f32_e32 v218, v218, v63
	v_cvt_pk_bf16_f32 v214, v56, v57
	v_cvt_pk_bf16_f32 v215, v58, v59
	v_cvt_pk_bf16_f32 v216, v60, v61
	v_cvt_pk_bf16_f32 v217, v62, v63
	s_setprio 0
	s_waitcnt lgkmcnt(0)
	s_barrier
	s_min_u32 s17, s12, 0xfb
	s_add_i32 s17, s17, 4
	s_mul_i32 s3, s17, 0x3000
	s_add_u32 s6, s42, s3
	s_addc_u32 s7, s43, 0
	s_lshl_b32 s90, s17, 13
	v_lshl_add_u64 v[182:183], v[162:163], 1, s[6:7]
	global_load_dwordx4 v[122:125], v[182:183], off
	s_and_saveexec_b64 s[8:9], s[4:5]
	s_cbranch_execz .Lattn_h1_nok1
	v_lshl_add_u64 v[182:183], s[6:7], 0, v[168:169]
	global_load_dwordx4 v[118:121], v[182:183], off
.Lattn_h1_nok1:
	s_or_b64 exec, exec, s[8:9]
	v_lshl_add_u64 v[182:183], v[164:165], 0, s[90:91]
	global_load_dwordx4 v[150:153], v[182:183], off
	s_setprio 1
	v_add3_u32 v177, s16, v174, v112
	v_add3_u32 v178, s15, v176, v112
	ds_read_b128 v[202:205], v177
	ds_read_b128 v[206:209], v177 offset:6656
	ds_read_b128 v[210:213], v177 offset:32
	v_mfma_f32_32x32x16_bf16 v[16:31], v[194:197], v[214:217], v[16:31]
	ds_read_b128 v[194:197], v177 offset:6688
	v_exp_f32_e32 v96, v96
	v_exp_f32_e32 v97, v97
	v_exp_f32_e32 v98, v98
	v_mfma_f32_32x32x16_bf16 v[0:15], v[198:201], v[214:217], v[0:15]
	ds_read_b128 v[198:201], v177 offset:64
	v_exp_f32_e32 v99, v99
	v_exp_f32_e32 v100, v100
	s_waitcnt lgkmcnt(4)
	v_mfma_f32_32x32x16_bf16 v[64:79], v[202:205], v[126:129], v[32:47]
	ds_read_b128 v[202:205], v177 offset:6720
	v_exp_f32_e32 v101, v101
	v_exp_f32_e32 v102, v102
	v_exp_f32_e32 v103, v103
	s_waitcnt lgkmcnt(4)
	v_mfma_f32_32x32x16_bf16 v[48:63], v[206:209], v[126:129], v[32:47]
	ds_read_b128 v[206:209], v177 offset:96
	v_exp_f32_e32 v104, v104
	v_add_f32_e32 v179, v179, v96
	v_exp_f32_e32 v105, v105
	s_waitcnt lgkmcnt(4)
	v_mfma_f32_32x32x16_bf16 v[64:79], v[210:213], v[130:133], v[64:79]
	ds_read_b128 v[210:213], v177 offset:6752
	v_add_f32_e32 v218, v218, v97
	v_exp_f32_e32 v106, v106
	v_add_f32_e32 v179, v179, v98
	s_waitcnt lgkmcnt(4)
	v_mfma_f32_32x32x16_bf16 v[48:63], v[194:197], v[130:133], v[48:63]
	ds_read_b128 v[194:197], v177 offset:128
	v_exp_f32_e32 v107, v107
	v_add_f32_e32 v218, v218, v99
	v_exp_f32_e32 v108, v108
	s_waitcnt lgkmcnt(4)
	v_mfma_f32_32x32x16_bf16 v[64:79], v[198:201], v[134:137], v[64:79]
	ds_read_b128 v[198:201], v177 offset:6784
	v_add_f32_e32 v179, v179, v100
	v_exp_f32_e32 v109, v109
	v_add_f32_e32 v218, v218, v101
	v_exp_f32_e32 v110, v110
	s_waitcnt lgkmcnt(4)
	v_mfma_f32_32x32x16_bf16 v[48:63], v[202:205], v[134:137], v[48:63]
	ds_read_b128 v[202:205], v177 offset:160
	v_add_f32_e32 v179, v179, v102
	v_exp_f32_e32 v111, v111
	s_waitcnt lgkmcnt(4)
	v_mfma_f32_32x32x16_bf16 v[64:79], v[206:209], v[138:141], v[64:79]
	ds_read_b128 v[206:209], v177 offset:6816
	v_add_f32_e32 v218, v218, v103
	v_cvt_pk_bf16_f32 v96, v96, v97
	v_cvt_pk_bf16_f32 v97, v98, v99
	v_cvt_pk_bf16_f32 v98, v100, v101
	v_cvt_pk_bf16_f32 v99, v102, v103
	v_add_u32_e32 v180, s14, v170
	s_waitcnt vmcnt(3)
	ds_write_b128 v180, v[158:161]
	s_and_saveexec_b64 s[6:7], s[4:5]
	v_add_u32_e32 v180, s14, v173
	ds_write_b128 v180, v[114:117]
	s_or_b64 exec, exec, s[6:7]
	v_add_u32_e32 v180, s14, v172
	v_add_u32_e32 v180, 0x3000, v180
	s_waitcnt vmcnt(2)
	ds_write2_b64 v180, v[154:155], v[156:157] offset0:128 offset1:130
	s_waitcnt lgkmcnt(6)
	v_mfma_f32_32x32x16_bf16 v[48:63], v[210:213], v[138:141], v[48:63]
	ds_read_b128 v[210:213], v178 offset:13312
	v_exp_f32_e32 v80, v80
	v_add_f32_e32 v179, v179, v104
	v_exp_f32_e32 v81, v81
	s_waitcnt lgkmcnt(6)
	v_mfma_f32_32x32x16_bf16 v[64:79], v[194:197], v[142:145], v[64:79]
	ds_read_b128 v[194:197], v178 offset:17920
	v_add_f32_e32 v218, v218, v105
	v_exp_f32_e32 v82, v82
	v_add_f32_e32 v179, v179, v106
	v_exp_f32_e32 v83, v83
	s_waitcnt lgkmcnt(6)
	v_mfma_f32_32x32x16_bf16 v[48:63], v[198:201], v[142:145], v[48:63]
	ds_read_b128 v[198:201], v178 offset:13344
	v_add_f32_e32 v218, v218, v107
	v_exp_f32_e32 v84, v84
	v_add_f32_e32 v179, v179, v108
	s_waitcnt lgkmcnt(6)
	v_mfma_f32_32x32x16_bf16 v[64:79], v[202:205], v[146:149], v[64:79]
	ds_read_b128 v[202:205], v178 offset:17952
	v_exp_f32_e32 v85, v85
	v_add_f32_e32 v218, v218, v109
	v_exp_f32_e32 v86, v86
	s_waitcnt lgkmcnt(6)
	v_mfma_f32_32x32x16_bf16 v[48:63], v[206:209], v[146:149], v[48:63]
	ds_read_b128 v[206:209], v178 offset:13376
	v_add_f32_e32 v179, v179, v110
	v_exp_f32_e32 v87, v87
	v_add_f32_e32 v218, v218, v111
	v_cvt_pk_bf16_f32 v104, v104, v105
	s_waitcnt lgkmcnt(4)
	v_mfma_f32_32x32x16_bf16 v[16:31], v[210:213], v[96:99], v[16:31]
	ds_read_b128 v[210:213], v178 offset:17984
	v_cvt_pk_bf16_f32 v105, v106, v107
	v_cvt_pk_bf16_f32 v106, v108, v109
	v_cvt_pk_bf16_f32 v107, v110, v111
	v_add_f32_e32 v179, v179, v80
	v_add_f32_e32 v218, v218, v81
	s_waitcnt lgkmcnt(4)
	v_mfma_f32_32x32x16_bf16 v[0:15], v[194:197], v[96:99], v[0:15]
	ds_read_b128 v[194:197], v178 offset:13408
	v_add_f32_e32 v179, v179, v82
	v_add_f32_e32 v218, v218, v83
	v_add_f32_e32 v179, v179, v84
	v_add_f32_e32 v218, v218, v85
	s_waitcnt lgkmcnt(4)
	v_mfma_f32_32x32x16_bf16 v[16:31], v[198:201], v[104:107], v[16:31]
	ds_read_b128 v[198:201], v178 offset:18016
	v_add_f32_e32 v179, v179, v86
	v_add_f32_e32 v218, v218, v87
	v_cvt_pk_bf16_f32 v80, v80, v81
	v_cvt_pk_bf16_f32 v81, v82, v83
	v_cvt_pk_bf16_f32 v82, v84, v85
	s_waitcnt lgkmcnt(4)
	v_mfma_f32_32x32x16_bf16 v[0:15], v[202:205], v[104:107], v[0:15]
	v_cvt_pk_bf16_f32 v83, v86, v87
	v_exp_f32_e32 v88, v88
	v_exp_f32_e32 v89, v89
	s_waitcnt lgkmcnt(3)
	v_mfma_f32_32x32x16_bf16 v[16:31], v[206:209], v[80:83], v[16:31]
	v_exp_f32_e32 v90, v90
	v_exp_f32_e32 v91, v91
	v_exp_f32_e32 v92, v92
	s_waitcnt lgkmcnt(2)
	v_mfma_f32_32x32x16_bf16 v[0:15], v[210:213], v[80:83], v[0:15]
	v_exp_f32_e32 v93, v93
	v_exp_f32_e32 v94, v94
	v_exp_f32_e32 v95, v95
	v_add_f32_e32 v179, v179, v88
	v_add_f32_e32 v218, v218, v89
	v_add_f32_e32 v179, v179, v90
	v_add_f32_e32 v218, v218, v91
	v_add_f32_e32 v179, v179, v92
	v_add_f32_e32 v218, v218, v93
	v_add_f32_e32 v179, v179, v94
	v_add_f32_e32 v218, v218, v95
	v_cvt_pk_bf16_f32 v214, v88, v89
	v_cvt_pk_bf16_f32 v215, v90, v91
	v_cvt_pk_bf16_f32 v216, v92, v93
	v_cvt_pk_bf16_f32 v217, v94, v95
	s_setprio 0
	s_cmpk_lt_u32 s12, 0xfe
	s_waitcnt lgkmcnt(0)
	s_barrier
	s_cbranch_scc0 .Lattn_exit
	s_mov_b32 s6, s11
	s_mov_b32 s11, s13
	s_branch .LBB0_1048
